# pool-branch weight fold moved to f32 MFMA (16x16x4), all loads of an item in one round trip
# speedup vs baseline: 1.0255x; 1.0255x over previous
; #define GAS __attribute__((address_space(1)))
; __device__ __forceinline__ unsigned pk2(float lo, float hi) { f32x2p v = {lo, hi}; bf16x2p b = __builtin_convertvector(v, bf16x2p); return __builtin_bit_cast(unsigned, b); }
; __device__ __forceinline__ void p0_pooleff_item(const float* wg, const float* scale, const float* wpb, bf16* WT, int item, int lane) {
;     const int nblk = item & 15, cblk = (item >> 4) & 15, g = item >> 8;
;     const int n = nblk * 64 + lane;
;     const float* wgp = wg + (size_t)(g * 128 + cblk * 8) * 128;
;     const float* bp = wpb + (size_t)(g * 128) * 1024 + n;
;     const float* sp = scale + g * 128;
;     float a0 = 0.f, a1 = 0.f, a2 = 0.f, a3 = 0.f, a4 = 0.f, a5 = 0.f, a6 = 0.f, a7 = 0.f;
; #pragma unroll 1
;     for (int j0 = 0; j0 < 128; j0 += 16) {
;         float b[16];
; #pragma unroll
;         for (int u = 0; u < 16; ++u) b[u] = bp[(size_t)(j0 + u) * 1024];
; #pragma unroll
;         for (int u = 0; u < 16; ++u) { const float bb = b[u] * sp[j0 + u];
;             a0 += wgp[0 * 128 + j0 + u] * bb; a1 += wgp[1 * 128 + j0 + u] * bb; a2 += wgp[2 * 128 + j0 + u] * bb; a3 += wgp[3 * 128 + j0 + u] * bb;
;             a4 += wgp[4 * 128 + j0 + u] * bb; a5 += wgp[5 * 128 + j0 + u] * bb; a6 += wgp[6 * 128 + j0 + u] * bb; a7 += wgp[7 * 128 + j0 + u] * bb; }
;     }
;     v4u o; o.x = pk2(a0, a1); o.y = pk2(a2, a3); o.z = pk2(a4, a5); o.w = pk2(a6, a7);
;     *(GAS v4u*)(WT + (size_t)n * 1024 + g * 128 + cblk * 8) = o;
; }
.LBB0_221:
	s_andn2_b64 vcc, exec, s[36:37]
	s_cbranch_vccnz .LBB0_173
	s_lshr_b32 s24, s23, 8
	s_bfe_u32 s25, s23, 0x30005
	s_and_b32 s26, s23, 31
	v_and_b32_e32 v2, 15, v67
	v_lshrrev_b32_e32 v3, 4, v67
	s_lshl_b32 s27, s24, 7
	s_lshl_b32 s28, s25, 4
	s_add_i32 s27, s27, s28
	s_lshl_b32 s27, s27, 9
	s_add_u32 s28, s42, s27
	s_addc_u32 s29, s43, 0
	v_lshlrev_b32_e32 v4, 9, v2
	v_lshl_add_u32 v4, v3, 7, v4
	s_lshl_b32 s27, s24, 9
	s_add_u32 s30, s44, s27
	s_addc_u32 s31, s45, 0
	v_lshlrev_b32_e32 v5, 7, v3
	s_lshl_b32 s38, s24, 19
	s_lshl_b32 s39, s26, 7
	s_add_i32 s38, s38, s39
	s_add_u32 s36, s46, s38
	s_addc_u32 s37, s47, 0
	v_lshlrev_b32_e32 v6, 17, v3
	v_lshl_add_u32 v6, v2, 2, v6
	global_load_dwordx4 v[8:11], v4, s[28:29] offset:0
	global_load_dwordx4 v[12:15], v4, s[28:29] offset:16
	global_load_dwordx4 v[16:19], v4, s[28:29] offset:32
	global_load_dwordx4 v[20:23], v4, s[28:29] offset:48
	global_load_dwordx4 v[24:27], v4, s[28:29] offset:64
	global_load_dwordx4 v[28:31], v4, s[28:29] offset:80
	global_load_dwordx4 v[32:35], v4, s[28:29] offset:96
	global_load_dwordx4 v[36:39], v4, s[28:29] offset:112
	global_load_dwordx4 v[128:131], v5, s[30:31] offset:0
	global_load_dwordx4 v[132:135], v5, s[30:31] offset:16
	global_load_dwordx4 v[136:139], v5, s[30:31] offset:32
	global_load_dwordx4 v[140:143], v5, s[30:31] offset:48
	global_load_dwordx4 v[144:147], v5, s[30:31] offset:64
	global_load_dwordx4 v[148:151], v5, s[30:31] offset:80
	global_load_dwordx4 v[152:155], v5, s[30:31] offset:96
	global_load_dwordx4 v[156:159], v5, s[30:31] offset:112
	global_load_dword v204, v6, s[36:37]
	global_load_dword v164, v6, s[36:37] offset:64
	s_add_u32 s36, s36, 0x1000
	s_addc_u32 s37, s37, 0
	global_load_dword v205, v6, s[36:37]
	global_load_dword v165, v6, s[36:37] offset:64
	s_add_u32 s36, s36, 0x1000
	s_addc_u32 s37, s37, 0
	global_load_dword v206, v6, s[36:37]
	global_load_dword v166, v6, s[36:37] offset:64
	s_add_u32 s36, s36, 0x1000
	s_addc_u32 s37, s37, 0
	global_load_dword v207, v6, s[36:37]
	global_load_dword v167, v6, s[36:37] offset:64
	s_add_u32 s36, s36, 0x1000
	s_addc_u32 s37, s37, 0
	global_load_dword v208, v6, s[36:37]
	global_load_dword v168, v6, s[36:37] offset:64
	s_add_u32 s36, s36, 0x1000
	s_addc_u32 s37, s37, 0
	global_load_dword v209, v6, s[36:37]
	global_load_dword v169, v6, s[36:37] offset:64
	s_add_u32 s36, s36, 0x1000
	s_addc_u32 s37, s37, 0
	global_load_dword v210, v6, s[36:37]
	global_load_dword v170, v6, s[36:37] offset:64
	s_add_u32 s36, s36, 0x1000
	s_addc_u32 s37, s37, 0
	global_load_dword v211, v6, s[36:37]
	global_load_dword v171, v6, s[36:37] offset:64
	s_add_u32 s36, s36, 0x1000
	s_addc_u32 s37, s37, 0
	global_load_dword v212, v6, s[36:37]
	global_load_dword v172, v6, s[36:37] offset:64
	s_add_u32 s36, s36, 0x1000
	s_addc_u32 s37, s37, 0
	global_load_dword v213, v6, s[36:37]
	global_load_dword v173, v6, s[36:37] offset:64
	s_add_u32 s36, s36, 0x1000
	s_addc_u32 s37, s37, 0
	global_load_dword v214, v6, s[36:37]
	global_load_dword v174, v6, s[36:37] offset:64
	s_add_u32 s36, s36, 0x1000
	s_addc_u32 s37, s37, 0
	global_load_dword v215, v6, s[36:37]
	global_load_dword v175, v6, s[36:37] offset:64
	s_add_u32 s36, s36, 0x1000
	s_addc_u32 s37, s37, 0
	global_load_dword v216, v6, s[36:37]
	global_load_dword v176, v6, s[36:37] offset:64
	s_add_u32 s36, s36, 0x1000
	s_addc_u32 s37, s37, 0
	global_load_dword v217, v6, s[36:37]
	global_load_dword v177, v6, s[36:37] offset:64
	s_add_u32 s36, s36, 0x1000
	s_addc_u32 s37, s37, 0
	global_load_dword v218, v6, s[36:37]
	global_load_dword v178, v6, s[36:37] offset:64
	s_add_u32 s36, s36, 0x1000
	s_addc_u32 s37, s37, 0
	global_load_dword v219, v6, s[36:37]
	global_load_dword v179, v6, s[36:37] offset:64
	s_add_u32 s36, s36, 0x1000
	s_addc_u32 s37, s37, 0
	global_load_dword v220, v6, s[36:37]
	global_load_dword v180, v6, s[36:37] offset:64
	s_add_u32 s36, s36, 0x1000
	s_addc_u32 s37, s37, 0
	global_load_dword v221, v6, s[36:37]
	global_load_dword v181, v6, s[36:37] offset:64
	s_add_u32 s36, s36, 0x1000
	s_addc_u32 s37, s37, 0
	global_load_dword v222, v6, s[36:37]
	global_load_dword v182, v6, s[36:37] offset:64
	s_add_u32 s36, s36, 0x1000
	s_addc_u32 s37, s37, 0
	global_load_dword v223, v6, s[36:37]
	global_load_dword v183, v6, s[36:37] offset:64
	s_add_u32 s36, s36, 0x1000
	s_addc_u32 s37, s37, 0
	global_load_dword v224, v6, s[36:37]
	global_load_dword v184, v6, s[36:37] offset:64
	s_add_u32 s36, s36, 0x1000
	s_addc_u32 s37, s37, 0
	global_load_dword v225, v6, s[36:37]
	global_load_dword v185, v6, s[36:37] offset:64
	s_add_u32 s36, s36, 0x1000
	s_addc_u32 s37, s37, 0
	global_load_dword v226, v6, s[36:37]
	global_load_dword v186, v6, s[36:37] offset:64
	s_add_u32 s36, s36, 0x1000
	s_addc_u32 s37, s37, 0
	global_load_dword v227, v6, s[36:37]
	global_load_dword v187, v6, s[36:37] offset:64
	s_add_u32 s36, s36, 0x1000
	s_addc_u32 s37, s37, 0
	global_load_dword v228, v6, s[36:37]
	global_load_dword v188, v6, s[36:37] offset:64
	s_add_u32 s36, s36, 0x1000
	s_addc_u32 s37, s37, 0
	global_load_dword v229, v6, s[36:37]
	global_load_dword v189, v6, s[36:37] offset:64
	s_add_u32 s36, s36, 0x1000
	s_addc_u32 s37, s37, 0
	global_load_dword v230, v6, s[36:37]
	global_load_dword v190, v6, s[36:37] offset:64
	s_add_u32 s36, s36, 0x1000
	s_addc_u32 s37, s37, 0
	global_load_dword v231, v6, s[36:37]
	global_load_dword v191, v6, s[36:37] offset:64
	s_add_u32 s36, s36, 0x1000
	s_addc_u32 s37, s37, 0
	global_load_dword v232, v6, s[36:37]
	global_load_dword v192, v6, s[36:37] offset:64
	s_add_u32 s36, s36, 0x1000
	s_addc_u32 s37, s37, 0
	global_load_dword v233, v6, s[36:37]
	global_load_dword v193, v6, s[36:37] offset:64
	s_add_u32 s36, s36, 0x1000
	s_addc_u32 s37, s37, 0
	global_load_dword v234, v6, s[36:37]
	global_load_dword v236, v6, s[36:37] offset:64
	s_add_u32 s36, s36, 0x1000
	s_addc_u32 s37, s37, 0
	global_load_dword v235, v6, s[36:37]
	global_load_dword v237, v6, s[36:37] offset:64
	s_lshl_b32 s38, s26, 16
	s_lshl_b32 s39, s24, 8
	s_add_i32 s38, s38, s39
	s_lshl_b32 s39, s25, 5
	s_add_i32 s38, s38, s39
	s_add_u32 s38, s56, s38
	s_addc_u32 s39, s57, 0
	v_lshlrev_b32_e32 v7, 11, v2
	v_lshl_add_u32 v7, v3, 3, v7
	v_mov_b32_e32 v40, 0
	v_mov_b32_e32 v41, 0
	v_mov_b32_e32 v42, 0
	v_mov_b32_e32 v43, 0
	v_mov_b32_e32 v44, 0
	v_mov_b32_e32 v45, 0
	v_mov_b32_e32 v46, 0
	v_mov_b32_e32 v47, 0
	s_waitcnt vmcnt(0)
; #define GAS __attribute__((address_space(1)))
; __device__ __forceinline__ unsigned pk2(float lo, float hi) { f32x2p v = {lo, hi}; bf16x2p b = __builtin_convertvector(v, bf16x2p); return __builtin_bit_cast(unsigned, b); }
; __device__ __forceinline__ void p0_pooleff_item(const float* wg, const float* scale, const float* wpb, bf16* WT, int item, int lane) {
;     ...
;         for (int u = 0; u < 16; ++u) { const float bb = b[u] * sp[j0 + u];
;             a0 += wgp[0 * 128 + j0 + u] * bb; a1 += wgp[1 * 128 + j0 + u] * bb; a2 += wgp[2 * 128 + j0 + u] * bb; a3 += wgp[3 * 128 + j0 + u] * bb;
;             a4 += wgp[4 * 128 + j0 + u] * bb; a5 += wgp[5 * 128 + j0 + u] * bb; a6 += wgp[6 * 128 + j0 + u] * bb; a7 += wgp[7 * 128 + j0 + u] * bb; }
;     }
;     v4u o; o.x = pk2(a0, a1); o.y = pk2(a2, a3); o.z = pk2(a4, a5); o.w = pk2(a6, a7);
;     *(GAS v4u*)(WT + (size_t)n * 1024 + g * 128 + cblk * 8) = o;
	v_mul_f32_e32 v8, v8, v128
	v_mul_f32_e32 v9, v9, v129
	v_mul_f32_e32 v10, v10, v130
	v_mul_f32_e32 v11, v11, v131
	v_mul_f32_e32 v12, v12, v132
	v_mul_f32_e32 v13, v13, v133
	v_mul_f32_e32 v14, v14, v134
	v_mul_f32_e32 v15, v15, v135
	v_mul_f32_e32 v16, v16, v136
	v_mul_f32_e32 v17, v17, v137
	v_mul_f32_e32 v18, v18, v138
	v_mul_f32_e32 v19, v19, v139
	v_mul_f32_e32 v20, v20, v140
	v_mul_f32_e32 v21, v21, v141
	v_mul_f32_e32 v22, v22, v142
	v_mul_f32_e32 v23, v23, v143
	v_mul_f32_e32 v24, v24, v144
	v_mul_f32_e32 v25, v25, v145
	v_mul_f32_e32 v26, v26, v146
	v_mul_f32_e32 v27, v27, v147
	v_mul_f32_e32 v28, v28, v148
	v_mul_f32_e32 v29, v29, v149
	v_mul_f32_e32 v30, v30, v150
	v_mul_f32_e32 v31, v31, v151
	v_mul_f32_e32 v32, v32, v152
	v_mul_f32_e32 v33, v33, v153
	v_mul_f32_e32 v34, v34, v154
	v_mul_f32_e32 v35, v35, v155
	v_mul_f32_e32 v36, v36, v156
	v_mul_f32_e32 v37, v37, v157
	v_mul_f32_e32 v38, v38, v158
	v_mul_f32_e32 v39, v39, v159
	s_nop 1
	v_mfma_f32_16x16x4_f32 v[40:43], v8, v204, v[40:43]
	v_mfma_f32_16x16x4_f32 v[44:47], v8, v164, v[44:47]
	v_mfma_f32_16x16x4_f32 v[40:43], v9, v205, v[40:43]
	v_mfma_f32_16x16x4_f32 v[44:47], v9, v165, v[44:47]
	v_mfma_f32_16x16x4_f32 v[40:43], v10, v206, v[40:43]
	v_mfma_f32_16x16x4_f32 v[44:47], v10, v166, v[44:47]
	v_mfma_f32_16x16x4_f32 v[40:43], v11, v207, v[40:43]
	v_mfma_f32_16x16x4_f32 v[44:47], v11, v167, v[44:47]
	v_mfma_f32_16x16x4_f32 v[40:43], v12, v208, v[40:43]
	v_mfma_f32_16x16x4_f32 v[44:47], v12, v168, v[44:47]
	v_mfma_f32_16x16x4_f32 v[40:43], v13, v209, v[40:43]
	v_mfma_f32_16x16x4_f32 v[44:47], v13, v169, v[44:47]
	v_mfma_f32_16x16x4_f32 v[40:43], v14, v210, v[40:43]
	v_mfma_f32_16x16x4_f32 v[44:47], v14, v170, v[44:47]
	v_mfma_f32_16x16x4_f32 v[40:43], v15, v211, v[40:43]
	v_mfma_f32_16x16x4_f32 v[44:47], v15, v171, v[44:47]
	v_mfma_f32_16x16x4_f32 v[40:43], v16, v212, v[40:43]
	v_mfma_f32_16x16x4_f32 v[44:47], v16, v172, v[44:47]
	v_mfma_f32_16x16x4_f32 v[40:43], v17, v213, v[40:43]
	v_mfma_f32_16x16x4_f32 v[44:47], v17, v173, v[44:47]
	v_mfma_f32_16x16x4_f32 v[40:43], v18, v214, v[40:43]
	v_mfma_f32_16x16x4_f32 v[44:47], v18, v174, v[44:47]
	v_mfma_f32_16x16x4_f32 v[40:43], v19, v215, v[40:43]
	v_mfma_f32_16x16x4_f32 v[44:47], v19, v175, v[44:47]
	v_mfma_f32_16x16x4_f32 v[40:43], v20, v216, v[40:43]
	v_mfma_f32_16x16x4_f32 v[44:47], v20, v176, v[44:47]
	v_mfma_f32_16x16x4_f32 v[40:43], v21, v217, v[40:43]
	v_mfma_f32_16x16x4_f32 v[44:47], v21, v177, v[44:47]
	v_mfma_f32_16x16x4_f32 v[40:43], v22, v218, v[40:43]
	v_mfma_f32_16x16x4_f32 v[44:47], v22, v178, v[44:47]
	v_mfma_f32_16x16x4_f32 v[40:43], v23, v219, v[40:43]
	v_mfma_f32_16x16x4_f32 v[44:47], v23, v179, v[44:47]
	v_mfma_f32_16x16x4_f32 v[40:43], v24, v220, v[40:43]
	v_mfma_f32_16x16x4_f32 v[44:47], v24, v180, v[44:47]
	v_mfma_f32_16x16x4_f32 v[40:43], v25, v221, v[40:43]
	v_mfma_f32_16x16x4_f32 v[44:47], v25, v181, v[44:47]
	v_mfma_f32_16x16x4_f32 v[40:43], v26, v222, v[40:43]
	v_mfma_f32_16x16x4_f32 v[44:47], v26, v182, v[44:47]
	v_mfma_f32_16x16x4_f32 v[40:43], v27, v223, v[40:43]
	v_mfma_f32_16x16x4_f32 v[44:47], v27, v183, v[44:47]
	v_mfma_f32_16x16x4_f32 v[40:43], v28, v224, v[40:43]
	v_mfma_f32_16x16x4_f32 v[44:47], v28, v184, v[44:47]
	v_mfma_f32_16x16x4_f32 v[40:43], v29, v225, v[40:43]
	v_mfma_f32_16x16x4_f32 v[44:47], v29, v185, v[44:47]
	v_mfma_f32_16x16x4_f32 v[40:43], v30, v226, v[40:43]
	v_mfma_f32_16x16x4_f32 v[44:47], v30, v186, v[44:47]
	v_mfma_f32_16x16x4_f32 v[40:43], v31, v227, v[40:43]
	v_mfma_f32_16x16x4_f32 v[44:47], v31, v187, v[44:47]
	v_mfma_f32_16x16x4_f32 v[40:43], v32, v228, v[40:43]
	v_mfma_f32_16x16x4_f32 v[44:47], v32, v188, v[44:47]
	v_mfma_f32_16x16x4_f32 v[40:43], v33, v229, v[40:43]
	v_mfma_f32_16x16x4_f32 v[44:47], v33, v189, v[44:47]
	v_mfma_f32_16x16x4_f32 v[40:43], v34, v230, v[40:43]
	v_mfma_f32_16x16x4_f32 v[44:47], v34, v190, v[44:47]
	v_mfma_f32_16x16x4_f32 v[40:43], v35, v231, v[40:43]
	v_mfma_f32_16x16x4_f32 v[44:47], v35, v191, v[44:47]
	v_mfma_f32_16x16x4_f32 v[40:43], v36, v232, v[40:43]
	v_mfma_f32_16x16x4_f32 v[44:47], v36, v192, v[44:47]
	v_mfma_f32_16x16x4_f32 v[40:43], v37, v233, v[40:43]
	v_mfma_f32_16x16x4_f32 v[44:47], v37, v193, v[44:47]
	v_mfma_f32_16x16x4_f32 v[40:43], v38, v234, v[40:43]
	v_mfma_f32_16x16x4_f32 v[44:47], v38, v236, v[44:47]
	v_mfma_f32_16x16x4_f32 v[40:43], v39, v235, v[40:43]
	v_mfma_f32_16x16x4_f32 v[44:47], v39, v237, v[44:47]
	s_nop 15
	s_nop 3
	v_cvt_pk_bf16_f32 v48, v40, v41
	v_cvt_pk_bf16_f32 v49, v42, v43
	v_cvt_pk_bf16_f32 v50, v44, v45
	v_cvt_pk_bf16_f32 v51, v46, v47
	global_store_dwordx2 v7, v[48:49], s[38:39]
	s_add_u32 s38, s38, 0x8000
	s_addc_u32 s39, s39, 0
	global_store_dwordx2 v7, v[50:51], s[38:39]
	s_branch .LBB0_173
